# v32: ssd_out head loop prefetches next iteration's z tile (issued after dt loads, staged to LDS at end of previous iteration)
# speedup vs baseline: 1.0101x; 1.0031x over previous
.LBB0_1334:
	s_or_b64 exec, exec, s[0:1]
	v_or_b32_e32 v70, s34, v157
	s_lshr_b32 s1, s74, 1
	v_or_b32_e32 v66, s72, v70
	s_lshr_b32 s0, s74, 2
	v_writelane_b32 v255, s34, 49
	v_ashrrev_i32_e32 v67, 31, v66
	s_and_b32 s42, s1, 1
	v_lshlrev_b64 v[66:67], 6, v[66:67]
	s_and_b32 s0, s0, 31
	s_lshl_b32 s43, s42, 3
	v_readlane_b32 s1, v255, 31
	v_readlane_b32 s56, v254, 46
	v_lshl_add_u64 v[66:67], s[28:29], 0, v[66:67]
	s_lshl_b32 s52, s18, 2
	s_lshl_b32 s40, s0, 7
	s_lshl_b32 s41, s0, 4
	s_add_i32 s0, s1, s43
	v_readlane_b32 s64, v254, 54
	v_readlane_b32 s65, v254, 55
	v_lshl_add_u64 v[66:67], v[66:67], 0, s[52:53]
	s_lshl_b32 s52, s42, 10
	s_lshl_b32 s0, s0, 2
	s_mov_b64 s[20:21], s[64:65]
	s_add_u32 s54, s20, s0
	v_or_b32_e32 v72, 1, v70
	v_cmp_gt_u32_e32 vcc, v160, v70
	s_addc_u32 s55, s21, 0
	v_or_b32_e32 v73, 2, v70
	s_or_b64 s[82:83], s[2:3], vcc
	v_cmp_gt_u32_e32 vcc, v160, v72
	v_or_b32_e32 v74, 3, v70
	s_or_b64 s[86:87], s[2:3], vcc
	v_cmp_gt_u32_e32 vcc, v160, v73
	s_or_b64 s[88:89], s[2:3], vcc
	v_cmp_gt_u32_e32 vcc, v160, v74
	s_or_b64 s[90:91], s[2:3], vcc
	v_cmp_gt_u32_e64 s[2:3], v161, v70
	v_readlane_b32 s57, v254, 47
	v_readlane_b32 s58, v254, 48
	v_readlane_b32 s59, v254, 49
	v_readlane_b32 s60, v254, 50
	v_readlane_b32 s61, v254, 51
	v_readlane_b32 s62, v254, 52
	v_readlane_b32 s63, v254, 53
	v_readlane_b32 s66, v254, 56
	v_readlane_b32 s67, v254, 57
	v_readlane_b32 s68, v254, 58
	v_readlane_b32 s69, v254, 59
	v_readlane_b32 s70, v254, 60
	v_readlane_b32 s71, v254, 61
	v_writelane_b32 v254, s2, 25
	v_writelane_b32 v255, s30, 50
	s_lshl_b32 s0, s1, 2
	v_writelane_b32 v254, s3, 26
	v_cmp_gt_u32_e64 s[2:3], v161, v72
	v_writelane_b32 v255, s31, 51
	s_cmp_gt_u32 s38, 1
	v_writelane_b32 v254, s2, 7
	v_cmp_gt_u32_e32 vcc, v162, v70
	s_cselect_b64 s[94:95], -1, 0
	v_writelane_b32 v254, s3, 8
	v_cmp_gt_u32_e64 s[2:3], v161, v73
	s_mov_b32 s1, s53
	v_lshl_add_u64 v[130:131], v[66:67], 0, s[0:1]
	v_writelane_b32 v255, s2, 19
	v_cndmask_b32_e64 v68, 0, 1, s[30:31]
	v_lshlrev_b32_e32 v69, 6, v68
	v_writelane_b32 v255, s3, 20
	v_cmp_gt_u32_e64 s[2:3], v161, v74
	v_lshl_add_u32 v115, v68, 11, v177
	v_or_b32_e32 v68, s40, v69
	v_writelane_b32 v255, s2, 21
	v_mul_u32_u24_e32 v71, 0x110, v70
	v_mov_b32_e32 v134, 0
	v_writelane_b32 v255, s3, 22
	s_or_b64 s[2:3], s[4:5], vcc
	v_writelane_b32 v255, s2, 17
	v_cmp_gt_u32_e32 vcc, v162, v72
	v_cmp_gt_u32_e64 s[0:1], v1, v70
	v_writelane_b32 v255, s3, 18
	s_or_b64 s[2:3], s[4:5], vcc
	v_writelane_b32 v255, s2, 23
	v_cmp_gt_u32_e32 vcc, v162, v73
	v_cmp_gt_u32_e64 s[18:19], v1, v72
	v_writelane_b32 v255, s3, 24
	s_or_b64 s[2:3], s[4:5], vcc
	v_writelane_b32 v255, s2, 52
	v_cmp_gt_u32_e32 vcc, v162, v74
	v_cmp_gt_u32_e64 s[20:21], v1, v73
	v_writelane_b32 v255, s3, 53
	s_or_b64 s[2:3], s[4:5], vcc
	v_cmp_gt_u32_e32 vcc, v164, v70
	v_writelane_b32 v255, s2, 54
	s_or_b64 s[80:81], s[16:17], vcc
	v_cmp_gt_u32_e32 vcc, v164, v72
	v_writelane_b32 v255, s3, 55
	s_or_b64 s[2:3], s[16:17], vcc
	v_cmp_gt_u32_e32 vcc, v164, v73
	s_or_b64 s[68:69], s[16:17], vcc
	v_cmp_gt_u32_e32 vcc, v164, v74
	s_or_b64 s[62:63], s[16:17], vcc
	s_cmp_gt_u32 s38, 5
	v_cmp_gt_u32_e32 vcc, v166, v70
	s_cselect_b64 s[56:57], -1, 0
	s_or_b64 s[16:17], s[36:37], vcc
	v_cmp_gt_u32_e32 vcc, v166, v72
	s_or_b64 s[4:5], s[36:37], vcc
	v_cmp_gt_u32_e32 vcc, v166, v73
	s_or_b64 s[60:61], s[36:37], vcc
	v_cmp_gt_u32_e32 vcc, v166, v74
	s_or_b64 s[58:59], s[36:37], vcc
	s_and_b32 s36, s38, 6
	s_cmp_eq_u32 s36, 6
	s_cselect_b64 s[84:85], -1, 0
	s_add_i32 s36, s40, s33
	v_add_u32_e32 v66, s36, v105
	v_ashrrev_i32_e32 v67, 31, v66
	v_lshlrev_b64 v[136:137], 6, v[66:67]
	s_add_i32 s38, s39, s41
	v_or_b32_e32 v67, v104, v136
	s_add_i32 s38, s38, s43
	v_lshl_or_b32 v136, s42, 5, v67
	v_mad_i64_i32 v[66:67], s[42:43], v66, s44, 0
	v_or_b32_e32 v66, v108, v66
	v_lshl_add_u64 v[138:139], v[66:67], 0, s[52:53]
	v_add_u32_e32 v66, s33, v68
	v_add_u32_e32 v66, v66, v176
	v_ashrrev_i32_e32 v67, 31, v66
	s_ashr_i32 s39, s38, 31
	v_lshlrev_b64 v[68:69], 12, v[66:67]
	s_movk_i32 s33, 0x2e00
	s_lshl_b64 s[38:39], s[38:39], 14
	v_lshl_add_u64 v[68:69], v[110:111], 0, v[68:69]
	v_mad_i64_i32 v[66:67], s[42:43], v66, s33, v[110:111]
	v_cmp_gt_u32_e64 s[22:23], v1, v74
	v_cmp_gt_u32_e64 s[34:35], v163, v70
	v_cmp_gt_u32_e64 s[30:31], v163, v72
	v_mov_b32_e32 v133, s39
	v_or_b32_e32 v132, s38, v106
	v_cmp_gt_u32_e64 s[92:93], v163, v73
	v_cmp_gt_u32_e64 s[96:97], v163, v74
	v_lshl_add_u64 v[142:143], v[68:69], 0, s[52:53]
	v_lshl_add_u64 v[144:145], v[66:67], 0, s[52:53]
	v_readlane_b32 s98, v255, 13
	v_readlane_b32 s99, v255, 14
	s_mov_b64 s[100:101], 0x8c01800
	s_nop 0
	v_lshl_add_u64 v[234:235], s[98:99], 0, v[144:145]
	v_lshl_add_u64 v[236:237], v[234:235], 0, s[100:101]
	global_load_dwordx4 v[226:229], v[236:237], off
	s_mov_b64 s[100:101], 0x8c18800
	v_lshl_add_u64 v[236:237], v[234:235], 0, s[100:101]
	global_load_dwordx4 v[230:233], v[236:237], off
	s_mov_b32 s33, 0
	v_add_u32_e32 v117, v159, v71
	v_mov_b32_e32 v135, v134
	v_mov_b32_e32 v140, v134
	v_mov_b32_e32 v141, v134
	v_cmp_gt_u32_e64 s[78:79], v165, v70
	v_cmp_gt_u32_e64 s[24:25], v165, v72
	v_cmp_gt_u32_e64 s[26:27], v165, v73
	v_cmp_gt_u32_e64 s[28:29], v165, v74
	s_mov_b64 s[64:65], 0
	s_waitcnt vmcnt(0)
	ds_write_b128 v158, v[62:65] offset:26112
	ds_write_b128 v180, v[226:229]
	ds_write_b128 v180, v[230:233] offset:1024
	s_branch .LBB0_1337

.LBB0_1346:
	v_readlane_b32 s36, v254, 63
	v_readlane_b32 s50, v255, 13
	v_readlane_b32 s51, v255, 14
	v_readlane_b32 s37, v255, 0
	v_readlane_b32 s38, v255, 1
	v_lshl_add_u64 v[66:67], s[70:71], 2, v[130:131]
	global_load_dword v84, v[66:67], off
	global_load_dword v85, v[66:67], off offset:64
	global_load_dword v82, v[66:67], off offset:128
	global_load_dword v83, v[66:67], off offset:192
	v_lshl_add_u64 v[70:71], s[50:51], 0, v[144:145]
	v_lshl_add_u64 v[70:71], v[70:71], 0, s[76:77]
	v_add_co_u32_e32 v66, vcc, 0x8c01000, v70
	v_readlane_b32 s39, v255, 2
	s_nop 0
	v_addc_co_u32_e32 v67, vcc, 0, v71, vcc
	v_add_co_u32_e32 v70, vcc, 0x8c18000, v70
	global_load_dwordx4 v[226:229], v[66:67], off offset:2048
	s_nop 0
	v_addc_co_u32_e32 v71, vcc, 0, v71, vcc
	global_load_dwordx4 v[230:233], v[70:71], off offset:2048
	s_and_b64 vcc, exec, s[6:7]
	v_readlane_b32 s40, v255, 3
	v_readlane_b32 s41, v255, 4
	v_readlane_b32 s42, v255, 5
	v_readlane_b32 s43, v255, 6
	v_readlane_b32 s44, v255, 7
	v_readlane_b32 s45, v255, 8
	v_readlane_b32 s46, v255, 9
	v_readlane_b32 s47, v255, 10
	v_readlane_b32 s48, v255, 11
	v_readlane_b32 s49, v255, 12
	v_add_u32_e32 v66, s33, v115
	v_add_u32_e32 v67, 0x1dc00, v66
	s_waitcnt lgkmcnt(0)
	s_barrier
	ds_read_b32 v152, v67
	v_add_u32_e32 v67, 0x1dc20, v66
	ds_read_b32 v153, v67
	v_add_u32_e32 v67, 0x1dc40, v66
	v_add_u32_e32 v66, 0x1dc60, v66
	ds_read_b32 v121, v67
	ds_read_b32 v119, v66
	v_add_u32_e32 v66, s33, v175
	v_add_u32_e32 v67, 0x1dc00, v66
	ds_read_b32 v67, v67
	s_waitcnt lgkmcnt(0)
	v_sub_f32_e32 v68, v152, v67
	v_mul_f32_e32 v68, 0x3fb8aa3b, v68
	v_exp_f32_e32 v68, v68
	s_nop 0
	v_mul_f32_e32 v68, v30, v68
	v_cvt_pk_bf16_f32 v68, v68, s0
	v_cndmask_b32_e64 v68, v68, 0, s[0:1]
	ds_write_b16 v181, v68
	v_sub_f32_e32 v68, v153, v67
	v_mul_f32_e32 v68, 0x3fb8aa3b, v68
	v_exp_f32_e32 v68, v68
	s_nop 0
	v_mul_f32_e32 v68, v31, v68
	v_cvt_pk_bf16_f32 v68, v68, s0
	v_cndmask_b32_e64 v68, v68, 0, s[18:19]
	ds_write_b16 v181, v68 offset:272
	v_sub_f32_e32 v68, v121, v67
	v_sub_f32_e32 v67, v119, v67
	v_mul_f32_e32 v67, 0x3fb8aa3b, v67
	v_exp_f32_e32 v67, v67
	v_mul_f32_e32 v68, 0x3fb8aa3b, v68
	v_exp_f32_e32 v68, v68
	v_mul_f32_e32 v67, v33, v67
	v_cvt_pk_bf16_f32 v67, v67, s0
	v_cndmask_b32_e64 v67, v67, 0, s[22:23]
	ds_write_b16 v181, v67 offset:816
	v_add_u32_e32 v67, 0x1de00, v66
	ds_read_b32 v67, v67
	v_mul_f32_e32 v68, v32, v68
	v_cvt_pk_bf16_f32 v68, v68, s0
	v_cndmask_b32_e64 v68, v68, 0, s[20:21]
	ds_write_b16 v181, v68 offset:544
	s_waitcnt lgkmcnt(1)
	v_sub_f32_e32 v68, v152, v67
	v_mul_f32_e32 v68, 0x3fb8aa3b, v68
	v_exp_f32_e32 v68, v68
	s_nop 0
	v_mul_f32_e32 v68, v2, v68
	v_cvt_pk_bf16_f32 v68, v68, s0
	v_cndmask_b32_e64 v68, v68, 0, s[82:83]
	ds_write_b16 v181, v68 offset:32
	v_sub_f32_e32 v68, v153, v67
	v_mul_f32_e32 v68, 0x3fb8aa3b, v68
	v_exp_f32_e32 v68, v68
	s_nop 0
	v_mul_f32_e32 v68, v3, v68
	v_cvt_pk_bf16_f32 v68, v68, s0
	v_cndmask_b32_e64 v68, v68, 0, s[86:87]
	ds_write_b16 v181, v68 offset:304
	v_sub_f32_e32 v68, v121, v67
	v_sub_f32_e32 v67, v119, v67
	v_mul_f32_e32 v68, 0x3fb8aa3b, v68
	v_mul_f32_e32 v67, 0x3fb8aa3b, v67
	v_exp_f32_e32 v68, v68
	v_exp_f32_e32 v67, v67
	v_mul_f32_e32 v68, v4, v68
	v_mul_f32_e32 v67, v5, v67
	v_cvt_pk_bf16_f32 v68, v68, s0
	v_cvt_pk_bf16_f32 v67, v67, s0
	v_cndmask_b32_e64 v68, v68, 0, s[88:89]
	v_cndmask_b32_e64 v67, v67, 0, s[90:91]
	ds_write_b16 v181, v68 offset:576
	ds_write_b16 v181, v67 offset:848
	s_cbranch_vccnz .LBB0_1350
	v_add_u32_e32 v67, 0x1e000, v66
	ds_read_b32 v67, v67
	v_readlane_b32 s36, v254, 25
	v_readlane_b32 s37, v254, 26
	s_waitcnt lgkmcnt(0)
	v_sub_f32_e32 v68, v152, v67
	v_mul_f32_e32 v68, 0x3fb8aa3b, v68
	v_exp_f32_e32 v68, v68
	s_nop 0
	v_mul_f32_e32 v68, v6, v68
	v_cvt_pk_bf16_f32 v68, v68, s0
	v_cndmask_b32_e64 v68, v68, 0, s[36:37]
	ds_write_b16 v181, v68 offset:64
	v_sub_f32_e32 v68, v153, v67
	v_mul_f32_e32 v68, 0x3fb8aa3b, v68
	v_exp_f32_e32 v68, v68
	v_readlane_b32 s36, v254, 7
	v_readlane_b32 s37, v254, 8
	v_mul_f32_e32 v68, v7, v68
	v_cvt_pk_bf16_f32 v68, v68, s0
	v_cndmask_b32_e64 v68, v68, 0, s[36:37]
	ds_write_b16 v181, v68 offset:336
	v_sub_f32_e32 v68, v121, v67
	v_mul_f32_e32 v68, 0x3fb8aa3b, v68
	v_exp_f32_e32 v68, v68
	v_sub_f32_e32 v67, v119, v67
	v_mul_f32_e32 v67, 0x3fb8aa3b, v67
	v_exp_f32_e32 v67, v67
	v_mul_f32_e32 v68, v8, v68
	v_readlane_b32 s36, v255, 19
	v_cvt_pk_bf16_f32 v68, v68, s0
	v_readlane_b32 s37, v255, 20
	v_mul_f32_e32 v67, v9, v67
	v_cvt_pk_bf16_f32 v67, v67, s0
	v_cndmask_b32_e64 v68, v68, 0, s[36:37]
	v_readlane_b32 s36, v255, 21
	v_readlane_b32 s37, v255, 22
	ds_write_b16 v181, v68 offset:608
	s_nop 0
	v_cndmask_b32_e64 v67, v67, 0, s[36:37]
	ds_write_b16 v181, v67 offset:880
	s_andn2_b64 vcc, exec, s[94:95]
	s_cbranch_vccz .LBB0_1351

.LBB0_1358:
	s_waitcnt vmcnt(4)
	v_div_scale_f32 v86, s[70:71], v85, v85, 1.0
	v_rcp_f32_e32 v87, v86
	v_add_u32_e32 v148, s73, v125
	ds_read_b128 v[184:187], v148 offset:65280
	v_mul_f32_e32 v152, 0x3fb8aa3b, v152
	v_fma_f32 v88, -v86, v87, 1.0
	v_fmac_f32_e32 v87, v88, v87
	v_div_scale_f32 v88, vcc, 1.0, v85, 1.0
	v_mul_f32_e32 v89, v88, v87
	v_fma_f32 v90, -v86, v89, v88
	v_fmac_f32_e32 v89, v90, v87
	v_fma_f32 v86, -v86, v89, v88
	v_div_fmas_f32 v86, v86, v87, v89
	v_div_fixup_f32 v151, v86, v85, 1.0
	v_div_scale_f32 v85, s[70:71], v84, v84, 1.0
	v_rcp_f32_e32 v86, v85
	ds_read_b128 v[90:93], v148 offset:56576
	ds_read_b128 v[94:97], v148 offset:60928
	v_mul_f32_e32 v153, 0x3fb8aa3b, v153
	v_fma_f32 v87, -v85, v86, 1.0
	v_fmac_f32_e32 v86, v87, v86
	v_div_scale_f32 v87, vcc, 1.0, v84, 1.0
	v_mul_f32_e32 v88, v87, v86
	v_fma_f32 v89, -v85, v88, v87
	v_fmac_f32_e32 v88, v89, v86
	v_fma_f32 v85, -v85, v88, v87
	v_div_fmas_f32 v85, v85, v86, v88
	v_div_fixup_f32 v150, v85, v84, 1.0
	s_waitcnt vmcnt(2)
	v_div_scale_f32 v84, s[70:71], v83, v83, 1.0
	v_rcp_f32_e32 v85, v84
	v_exp_f32_e32 v152, v152
	v_exp_f32_e32 v153, v153
	v_readlane_b32 s36, v254, 63
	v_fma_f32 v86, -v84, v85, 1.0
	v_fmac_f32_e32 v85, v86, v85
	v_div_scale_f32 v86, vcc, 1.0, v83, 1.0
	v_mul_f32_e32 v87, v86, v85
	v_fma_f32 v88, -v84, v87, v86
	v_fmac_f32_e32 v87, v88, v85
	v_fma_f32 v84, -v84, v87, v86
	v_div_fmas_f32 v84, v84, v85, v87
	v_div_fixup_f32 v147, v84, v83, 1.0
	v_div_scale_f32 v83, s[70:71], v82, v82, 1.0
	v_rcp_f32_e32 v84, v83
	v_readlane_b32 s50, v255, 13
	v_readlane_b32 s51, v255, 14
	v_readlane_b32 s37, v255, 0
	v_fma_f32 v85, -v83, v84, 1.0
	v_fmac_f32_e32 v84, v85, v84
	v_div_scale_f32 v85, vcc, 1.0, v82, 1.0
	v_mul_f32_e32 v86, v85, v84
	v_fma_f32 v87, -v83, v86, v85
	v_fmac_f32_e32 v86, v87, v84
	v_fma_f32 v83, -v83, v86, v85
	v_div_fmas_f32 v83, v83, v84, v86
	v_div_fixup_f32 v146, v83, v82, 1.0
	ds_read_b128 v[82:85], v113
	ds_read_b128 v[86:89], v148 offset:52224
	s_waitcnt lgkmcnt(0)
	v_mfma_f32_16x16x32_bf16 v[86:89], v[82:85], v[86:89], 0
	v_readlane_b32 s38, v255, 1
	v_readlane_b32 s39, v255, 2
	v_readlane_b32 s40, v255, 3
	v_mfma_f32_16x16x32_bf16 v[90:93], v[82:85], v[90:93], 0
	v_readlane_b32 s41, v255, 4
	v_readlane_b32 s42, v255, 5
	v_readlane_b32 s43, v255, 6
	v_mfma_f32_16x16x32_bf16 v[94:97], v[82:85], v[94:97], 0
	v_readlane_b32 s44, v255, 7
	v_readlane_b32 s45, v255, 8
	v_readlane_b32 s46, v255, 9
	v_mfma_f32_16x16x32_bf16 v[82:85], v[82:85], v[184:187], 0
	ds_read_b128 v[184:187], v113 offset:64
	ds_read_b128 v[188:191], v148 offset:52288
	v_readlane_b32 s47, v255, 10
	v_readlane_b32 s48, v255, 11
	s_waitcnt lgkmcnt(0)
	v_mfma_f32_16x16x32_bf16 v[86:89], v[184:187], v[188:191], v[86:89]
	ds_read_b128 v[188:191], v148 offset:56640
	v_readlane_b32 s49, v255, 12
	s_waitcnt lgkmcnt(0)
	v_mfma_f32_16x16x32_bf16 v[90:93], v[184:187], v[188:191], v[90:93]
	ds_read_b128 v[188:191], v148 offset:60992
	s_waitcnt lgkmcnt(0)
	v_mfma_f32_16x16x32_bf16 v[94:97], v[184:187], v[188:191], v[94:97]
	ds_read_b128 v[188:191], v148 offset:65344
	s_waitcnt lgkmcnt(0)
	v_mfma_f32_16x16x32_bf16 v[82:85], v[184:187], v[188:191], v[82:85]
	ds_read_b128 v[184:187], v113 offset:128
	ds_read_b128 v[188:191], v148 offset:52352
	s_waitcnt lgkmcnt(0)
	v_mfma_f32_16x16x32_bf16 v[86:89], v[184:187], v[188:191], v[86:89]
	ds_read_b128 v[188:191], v148 offset:56704
	s_waitcnt lgkmcnt(0)
	v_mfma_f32_16x16x32_bf16 v[90:93], v[184:187], v[188:191], v[90:93]
	ds_read_b128 v[188:191], v148 offset:61056
	s_waitcnt lgkmcnt(0)
	v_mfma_f32_16x16x32_bf16 v[188:191], v[184:187], v[188:191], v[94:97]
	s_nop 2
	ds_read_b128 v[94:97], v148 offset:65408
	s_waitcnt lgkmcnt(0)
	v_mfma_f32_16x16x32_bf16 v[82:85], v[184:187], v[94:97], v[82:85]
	ds_read_b128 v[184:187], v113 offset:192
	ds_read_b128 v[94:97], v148 offset:52416
	s_waitcnt lgkmcnt(0)
	v_mfma_f32_16x16x32_bf16 v[94:97], v[184:187], v[94:97], v[86:89]
	s_nop 2
	ds_read_b128 v[86:89], v148 offset:56768
	s_waitcnt lgkmcnt(0)
	v_mfma_f32_16x16x32_bf16 v[90:93], v[184:187], v[86:89], v[90:93]
	ds_read_b128 v[86:89], v148 offset:61120
	s_nop 0
	v_pk_fma_f32 v[78:79], v[152:153], v[94:95], v[78:79]
	s_nop 4
	v_pk_fma_f32 v[90:91], v[152:153], v[90:91], v[74:75]
	s_waitcnt lgkmcnt(0)
	v_mfma_f32_16x16x32_bf16 v[86:89], v[184:187], v[86:89], v[188:191]
	s_nop 2
	ds_read_b128 v[188:191], v148 offset:65472
	global_load_dword v148, v99, s[54:55]
	s_waitcnt lgkmcnt(0)
	v_mfma_f32_16x16x32_bf16 v[82:85], v[184:187], v[188:191], v[82:85]
	ds_read_u16 v183, v117 offset:17408
	ds_read_u16 v187, v117 offset:17440
	ds_read_u16 v184, v178
	ds_read_u16 v185, v178 offset:32
	ds_read_u16 v190, v117 offset:17472
	ds_read_u16 v191, v178 offset:64
	ds_read_u16 v192, v117 offset:17504
	ds_read_u16 v186, v178 offset:96
	ds_read_u16 v188, v117 offset:17680
	ds_read_u16 v189, v178 offset:128
	ds_read_u16 v193, v117 offset:17712
	ds_read_u16 v194, v178 offset:160
	ds_read_u16 v195, v117 offset:17744
	ds_read_u16 v196, v178 offset:192
	ds_read_u16 v197, v117 offset:17776
	ds_read_u16 v198, v178 offset:224
	s_waitcnt lgkmcnt(13)
	v_lshlrev_b32_e32 v200, 16, v184
	s_waitcnt lgkmcnt(12)
	v_lshlrev_b32_e32 v201, 16, v185
	v_mul_f32_e32 v184, 0xbfb8aa3b, v200
	v_mul_f32_e32 v185, 0xbfb8aa3b, v201
	s_waitcnt lgkmcnt(8)
	v_lshlrev_b32_e32 v199, 16, v186
	v_exp_f32_e32 v184, v184
	v_exp_f32_e32 v186, v185
	s_waitcnt lgkmcnt(4)
	v_lshlrev_b32_e32 v194, 16, v194
	v_mul_f32_e32 v74, 0xbfb8aa3b, v194
	v_pk_fma_f32 v[70:71], v[152:153], v[86:87], v[70:71]
	s_waitcnt lgkmcnt(0)
	v_lshlrev_b32_e32 v198, 16, v198
	v_pk_fma_f32 v[66:67], v[152:153], v[82:83], v[66:67]
	v_mul_f32_e32 v82, 0xbfb8aa3b, v198
	s_waitcnt vmcnt(0)
	v_pk_mul_f32 v[154:155], v[150:151], v[148:149] op_sel_hi:[1,0]
	v_lshlrev_b32_e32 v151, 16, v189
	v_mul_f32_e32 v94, 0xbfb8aa3b, v151
	v_exp_f32_e32 v185, v94
	v_lshlrev_b32_e32 v189, 16, v188
	v_lshlrev_b32_e32 v188, 16, v183
	v_mul_f32_e32 v150, 0xbfb8aa3b, v199
	v_pk_add_f32 v[94:95], v[184:185], 1.0 op_sel_hi:[1,0]
	v_exp_f32_e32 v150, v150
	v_div_scale_f32 v183, s[70:71], v95, v95, v151
	v_rcp_f32_e32 v184, v183
	s_nop 0
	v_fma_f32 v185, -v183, v184, 1.0
	v_fmac_f32_e32 v184, v185, v184
	v_div_scale_f32 v185, vcc, v151, v95, v151
	v_mul_f32_e32 v202, v185, v184
	v_fma_f32 v203, -v183, v202, v185
	v_fmac_f32_e32 v202, v203, v184
	v_fma_f32 v183, -v183, v202, v185
	v_div_fmas_f32 v183, v183, v184, v202
	v_div_fixup_f32 v95, v183, v95, v151
	v_div_scale_f32 v151, s[70:71], v94, v94, v200
	v_rcp_f32_e32 v183, v151
	s_nop 0
	v_fma_f32 v184, -v151, v183, 1.0
	v_fmac_f32_e32 v183, v184, v183
	v_div_scale_f32 v184, vcc, v200, v94, v200
	v_mul_f32_e32 v185, v184, v183
	v_fma_f32 v202, -v151, v185, v184
	v_fmac_f32_e32 v185, v202, v183
	v_fma_f32 v151, -v151, v185, v184
	v_lshlrev_b32_e32 v184, 16, v187
	v_exp_f32_e32 v187, v74
	v_div_fmas_f32 v151, v151, v183, v185
	v_div_fixup_f32 v94, v151, v94, v200
	v_lshlrev_b32_e32 v185, 16, v193
	v_pk_add_f32 v[74:75], v[186:187], 1.0 op_sel_hi:[1,0]
	s_nop 0
	v_div_scale_f32 v151, s[70:71], v75, v75, v194
	v_rcp_f32_e32 v183, v151
	s_nop 0
	v_fma_f32 v186, -v151, v183, 1.0
	v_fmac_f32_e32 v183, v186, v183
	v_div_scale_f32 v186, vcc, v194, v75, v194
	v_mul_f32_e32 v187, v186, v183
	v_fma_f32 v193, -v151, v187, v186
	v_fmac_f32_e32 v187, v193, v183
	v_fma_f32 v151, -v151, v187, v186
	v_div_fmas_f32 v151, v151, v183, v187
	v_div_fixup_f32 v187, v151, v75, v194
	v_div_scale_f32 v75, s[70:71], v74, v74, v201
	v_rcp_f32_e32 v151, v75
	s_nop 0
	v_fma_f32 v183, -v75, v151, 1.0
	v_fmac_f32_e32 v151, v183, v151
	v_div_scale_f32 v183, vcc, v201, v74, v201
	v_mul_f32_e32 v186, v183, v151
	v_fma_f32 v193, -v75, v186, v183
	v_fmac_f32_e32 v186, v193, v151
	v_fma_f32 v75, -v75, v186, v183
	v_div_fmas_f32 v75, v75, v151, v186
	v_lshlrev_b32_e32 v151, 16, v196
	v_lshlrev_b32_e32 v183, 16, v191
	v_div_fixup_f32 v186, v75, v74, v201
	v_pk_fma_f32 v[74:75], v[154:155], v[188:189], v[78:79]
	v_pk_fma_f32 v[78:79], v[154:155], v[184:185], v[90:91]
	v_mul_f32_e32 v90, 0xbfb8aa3b, v183
	v_mul_f32_e32 v86, 0xbfb8aa3b, v151
	v_exp_f32_e32 v90, v90
	v_exp_f32_e32 v91, v86
	v_pk_mul_f32 v[78:79], v[78:79], v[186:187]
	v_pk_mul_f32 v[74:75], v[74:75], v[94:95]
	v_lshlrev_b32_e32 v95, 16, v195
	v_pk_add_f32 v[86:87], v[90:91], 1.0 op_sel_hi:[1,0]
	v_lshlrev_b32_e32 v94, 16, v190
	v_div_scale_f32 v90, s[70:71], v87, v87, v151
	v_rcp_f32_e32 v91, v90
	v_pk_fma_f32 v[70:71], v[154:155], v[94:95], v[70:71]
	v_fma_f32 v184, -v90, v91, 1.0
	v_fmac_f32_e32 v91, v184, v91
	v_div_scale_f32 v184, vcc, v151, v87, v151
	v_mul_f32_e32 v185, v184, v91
	v_fma_f32 v186, -v90, v185, v184
	v_fmac_f32_e32 v185, v186, v91
	v_fma_f32 v90, -v90, v185, v184
	v_div_fmas_f32 v90, v90, v91, v185
	v_div_fixup_f32 v87, v90, v87, v151
	v_div_scale_f32 v90, s[70:71], v86, v86, v183
	v_rcp_f32_e32 v91, v90
	s_nop 0
	v_fma_f32 v151, -v90, v91, 1.0
	v_fmac_f32_e32 v91, v151, v91
	v_div_scale_f32 v151, vcc, v183, v86, v183
	v_mul_f32_e32 v184, v151, v91
	v_fma_f32 v185, -v90, v184, v151
	v_fmac_f32_e32 v184, v185, v91
	v_fma_f32 v90, -v90, v184, v151
	v_exp_f32_e32 v151, v82
	v_div_fmas_f32 v90, v90, v91, v184
	v_div_fixup_f32 v86, v90, v86, v183
	v_pk_mul_f32 v[70:71], v[70:71], v[86:87]
	v_lshlrev_b32_e32 v87, 16, v197
	v_lshlrev_b32_e32 v86, 16, v192
	v_pk_add_f32 v[82:83], v[150:151], 1.0 op_sel_hi:[1,0]
	v_pk_fma_f32 v[66:67], v[154:155], v[86:87], v[66:67]
	v_div_scale_f32 v86, s[70:71], v83, v83, v198
	v_rcp_f32_e32 v87, v86
	s_nop 0
	v_fma_f32 v90, -v86, v87, 1.0
	v_fmac_f32_e32 v87, v90, v87
	v_div_scale_f32 v90, vcc, v198, v83, v198
	v_mul_f32_e32 v91, v90, v87
	v_fma_f32 v94, -v86, v91, v90
	v_fmac_f32_e32 v91, v94, v87
	v_fma_f32 v86, -v86, v91, v90
	v_div_fmas_f32 v86, v86, v87, v91
	v_div_fixup_f32 v83, v86, v83, v198
	v_div_scale_f32 v86, s[70:71], v82, v82, v199
	v_rcp_f32_e32 v87, v86
	s_nop 0
	v_fma_f32 v90, -v86, v87, 1.0
	v_fmac_f32_e32 v87, v90, v87
	v_div_scale_f32 v90, vcc, v199, v82, v199
	v_mul_f32_e32 v91, v90, v87
	v_fma_f32 v94, -v86, v91, v90
	v_fmac_f32_e32 v91, v94, v87
	v_fma_f32 v86, -v86, v91, v90
	v_div_fmas_f32 v86, v86, v87, v91
	v_div_fixup_f32 v82, v86, v82, v199
	v_pk_mul_f32 v[66:67], v[66:67], v[82:83]
	v_mul_f32_e32 v82, 0x3fb8aa3b, v121
	ds_read_u16 v87, v117 offset:17952
	ds_read_u16 v94, v178 offset:256
	ds_read_u16 v121, v117 offset:17984
	ds_read_u16 v95, v178 offset:288
	ds_read_u16 v152, v117 offset:18016
	ds_read_u16 v153, v178 offset:320
	ds_read_u16 v154, v117 offset:18048
	ds_read_u16 v86, v178 offset:352
	v_mul_f32_e32 v83, 0x3fb8aa3b, v119
	ds_read_u16 v119, v117 offset:18224
	ds_read_u16 v150, v178 offset:384
	ds_read_u16 v155, v117 offset:18256
	ds_read_u16 v151, v178 offset:416
	ds_read_u16 v183, v117 offset:18288
	ds_read_u16 v184, v178 offset:448
	ds_read_u16 v185, v117 offset:18320
	ds_read_u16 v186, v178 offset:480
	v_pk_mul_f32 v[90:91], v[146:147], v[148:149] op_sel_hi:[1,0]
	s_waitcnt lgkmcnt(6)
	v_lshlrev_b32_e32 v147, 16, v150
	v_lshlrev_b32_e32 v187, 16, v94
	v_lshlrev_b32_e32 v189, 16, v95
	v_mul_f32_e32 v94, 0xbfb8aa3b, v187
	v_mul_f32_e32 v95, 0xbfb8aa3b, v189
	v_lshlrev_b32_e32 v150, 16, v87
	v_mul_f32_e32 v87, 0xbfb8aa3b, v147
	v_exp_f32_e32 v94, v94
	v_exp_f32_e32 v146, v95
	v_exp_f32_e32 v95, v87
	v_exp_f32_e32 v82, v82
	v_exp_f32_e32 v83, v83
	s_waitcnt lgkmcnt(4)
	v_lshlrev_b32_e32 v188, 16, v151
	v_pk_add_f32 v[94:95], v[94:95], 1.0 op_sel_hi:[1,0]
	v_lshlrev_b32_e32 v151, 16, v119
	v_div_scale_f32 v87, s[70:71], v95, v95, v147
	v_pk_fma_f32 v[80:81], v[82:83], v[96:97], v[80:81]
	v_rcp_f32_e32 v96, v87
	v_pk_fma_f32 v[92:93], v[82:83], v[92:93], v[76:77]
	v_mul_f32_e32 v76, 0xbfb8aa3b, v188
	v_pk_fma_f32 v[72:73], v[82:83], v[88:89], v[72:73]
	v_fma_f32 v97, -v87, v96, 1.0
	v_fmac_f32_e32 v96, v97, v96
	v_div_scale_f32 v97, vcc, v147, v95, v147
	v_mul_f32_e32 v119, v97, v96
	v_fma_f32 v190, -v87, v119, v97
	v_fmac_f32_e32 v119, v190, v96
	v_fma_f32 v87, -v87, v119, v97
	v_div_fmas_f32 v87, v87, v96, v119
	v_div_fixup_f32 v95, v87, v95, v147
	v_div_scale_f32 v87, s[70:71], v94, v94, v187
	v_rcp_f32_e32 v96, v87
	s_waitcnt lgkmcnt(0)
	v_lshlrev_b32_e32 v148, 16, v186
	v_lshlrev_b32_e32 v186, 16, v86
	v_mul_f32_e32 v86, 0xbfb8aa3b, v186
	v_fma_f32 v97, -v87, v96, 1.0
	v_fmac_f32_e32 v96, v97, v96
	v_div_scale_f32 v97, vcc, v187, v94, v187
	v_mul_f32_e32 v119, v97, v96
	v_fma_f32 v147, -v87, v119, v97
	v_fmac_f32_e32 v119, v147, v96
	v_exp_f32_e32 v147, v76
	v_fma_f32 v87, -v87, v119, v97
	v_div_fmas_f32 v87, v87, v96, v119
	v_div_fixup_f32 v94, v87, v94, v187
	v_pk_add_f32 v[76:77], v[146:147], 1.0 op_sel_hi:[1,0]
	v_lshlrev_b32_e32 v96, 16, v121
	v_div_scale_f32 v87, s[70:71], v77, v77, v188
	v_rcp_f32_e32 v119, v87
	v_lshlrev_b32_e32 v97, 16, v155
	v_pk_fma_f32 v[68:69], v[82:83], v[84:85], v[68:69]
	v_mul_f32_e32 v82, 0xbfb8aa3b, v148
	v_fma_f32 v121, -v87, v119, 1.0
	v_fmac_f32_e32 v119, v121, v119
	v_div_scale_f32 v121, vcc, v188, v77, v188
	v_mul_f32_e32 v146, v121, v119
	v_fma_f32 v147, -v87, v146, v121
	v_fmac_f32_e32 v146, v147, v119
	v_fma_f32 v87, -v87, v146, v121
	v_div_fmas_f32 v87, v87, v119, v146
	v_div_fixup_f32 v147, v87, v77, v188
	v_div_scale_f32 v77, s[70:71], v76, v76, v189
	v_rcp_f32_e32 v87, v77
	v_exp_f32_e32 v86, v86
	s_waitcnt lgkmcnt(0)
	v_fma_f32 v119, -v77, v87, 1.0
	v_fmac_f32_e32 v87, v119, v87
	v_div_scale_f32 v119, vcc, v189, v76, v189
	v_mul_f32_e32 v121, v119, v87
	v_fma_f32 v146, -v77, v121, v119
	v_fmac_f32_e32 v121, v146, v87
	v_fma_f32 v77, -v77, v121, v119
	v_div_fmas_f32 v77, v77, v87, v121
	v_div_fixup_f32 v146, v77, v76, v189
	v_pk_fma_f32 v[76:77], v[90:91], v[150:151], v[80:81]
	v_pk_fma_f32 v[80:81], v[90:91], v[96:97], v[92:93]
	v_lshlrev_b32_e32 v87, 16, v184
	v_lshlrev_b32_e32 v96, 16, v153
	v_mul_f32_e32 v92, 0xbfb8aa3b, v96
	v_mul_f32_e32 v88, 0xbfb8aa3b, v87
	v_exp_f32_e32 v92, v92
	v_exp_f32_e32 v93, v88
	v_pk_mul_f32 v[76:77], v[76:77], v[94:95]
	v_lshlrev_b32_e32 v95, 16, v183
	v_lshlrev_b32_e32 v94, 16, v152
	v_pk_add_f32 v[88:89], v[92:93], 1.0 op_sel_hi:[1,0]
	v_pk_fma_f32 v[72:73], v[90:91], v[94:95], v[72:73]
	v_div_scale_f32 v92, s[70:71], v89, v89, v87
	v_rcp_f32_e32 v93, v92
	v_pk_mul_f32 v[80:81], v[80:81], v[146:147]
	v_fma_f32 v97, -v92, v93, 1.0
	v_fmac_f32_e32 v93, v97, v93
	v_div_scale_f32 v97, vcc, v87, v89, v87
	v_mul_f32_e32 v119, v97, v93
	v_fma_f32 v121, -v92, v119, v97
	v_fmac_f32_e32 v119, v121, v93
	v_fma_f32 v92, -v92, v119, v97
	v_div_fmas_f32 v92, v92, v93, v119
	v_div_fixup_f32 v89, v92, v89, v87
	v_div_scale_f32 v87, s[70:71], v88, v88, v96
	v_rcp_f32_e32 v92, v87
	s_nop 0
	v_fma_f32 v93, -v87, v92, 1.0
	v_fmac_f32_e32 v92, v93, v92
	v_div_scale_f32 v93, vcc, v96, v88, v96
	v_mul_f32_e32 v97, v93, v92
	v_fma_f32 v119, -v87, v97, v93
	v_fmac_f32_e32 v97, v119, v92
	v_fma_f32 v87, -v87, v97, v93
	v_div_fmas_f32 v87, v87, v92, v97
	v_div_fixup_f32 v88, v87, v88, v96
	v_exp_f32_e32 v87, v82
	v_pk_mul_f32 v[72:73], v[72:73], v[88:89]
	v_lshlrev_b32_e32 v89, 16, v185
	v_lshlrev_b32_e32 v88, 16, v154
	v_pk_add_f32 v[82:83], v[86:87], 1.0 op_sel_hi:[1,0]
	v_pk_fma_f32 v[68:69], v[90:91], v[88:89], v[68:69]
	v_div_scale_f32 v84, s[70:71], v83, v83, v148
	v_rcp_f32_e32 v85, v84
	v_lshl_add_u64 v[90:91], s[50:51], 0, v[142:143]
	v_fma_f32 v86, -v84, v85, 1.0
	v_fmac_f32_e32 v85, v86, v85
	v_div_scale_f32 v86, vcc, v148, v83, v148
	v_mul_f32_e32 v87, v86, v85
	v_fma_f32 v88, -v84, v87, v86
	v_fmac_f32_e32 v87, v88, v85
	v_fma_f32 v84, -v84, v87, v86
	v_div_fmas_f32 v84, v84, v85, v87
	v_div_fixup_f32 v83, v84, v83, v148
	v_div_scale_f32 v84, s[70:71], v82, v82, v186
	v_rcp_f32_e32 v85, v84
	s_nop 0
	v_fma_f32 v86, -v84, v85, 1.0
	v_fmac_f32_e32 v85, v86, v85
	v_div_scale_f32 v86, vcc, v186, v82, v186
	v_mul_f32_e32 v87, v86, v85
	v_fma_f32 v88, -v84, v87, v86
	v_fmac_f32_e32 v87, v88, v85
	v_fma_f32 v84, -v84, v87, v86
	v_div_fmas_f32 v84, v84, v85, v87
	v_div_fixup_f32 v82, v84, v82, v186
	v_pk_mul_f32 v[68:69], v[68:69], v[82:83]
	v_cvt_pk_bf16_f32 v82, v74, s0
	ds_write_b16 v178, v82
	v_cvt_pk_bf16_f32 v82, v78, s0
	ds_write_b16 v178, v82 offset:32
	v_cvt_pk_bf16_f32 v82, v70, s0
	ds_write_b16 v178, v82 offset:64
	v_cvt_pk_bf16_f32 v82, v66, s0
	ds_write_b16 v178, v82 offset:96
	v_cvt_pk_bf16_f32 v82, v75, s0
	ds_write_b16 v178, v82 offset:128
	v_cvt_pk_bf16_f32 v82, v79, s0
	ds_write_b16 v178, v82 offset:160
	v_cvt_pk_bf16_f32 v82, v71, s0
	ds_write_b16 v178, v82 offset:192
	v_cvt_pk_bf16_f32 v82, v67, s0
	ds_write_b16 v178, v82 offset:224
	v_cvt_pk_bf16_f32 v82, v76, s0
	ds_write_b16 v178, v82 offset:256
	v_cvt_pk_bf16_f32 v82, v80, s0
	ds_write_b16 v178, v82 offset:288
	v_cvt_pk_bf16_f32 v82, v72, s0
	ds_write_b16 v178, v82 offset:320
	v_cvt_pk_bf16_f32 v82, v68, s0
	ds_write_b16 v178, v82 offset:352
	v_cvt_pk_bf16_f32 v82, v77, s0
	ds_write_b16 v178, v82 offset:384
	v_cvt_pk_bf16_f32 v82, v81, s0
	ds_write_b16 v178, v82 offset:416
	v_cvt_pk_bf16_f32 v82, v73, s0
	ds_write_b16 v178, v82 offset:448
	v_cvt_pk_bf16_f32 v82, v69, s0
	ds_write_b16 v178, v82 offset:480
	s_waitcnt lgkmcnt(0)
	ds_read_b128 v[82:85], v180
	ds_read_b128 v[86:89], v180 offset:1024
	v_add_co_u32_e32 v92, vcc, 0x10000000, v90
	s_nop 1
	v_addc_co_u32_e32 v93, vcc, 0, v91, vcc
	s_waitcnt lgkmcnt(1)
	global_store_dwordx4 v[92:93], v[82:85], off offset:2048
	s_nop 1
	v_add_co_u32_e32 v82, vcc, 0x10008000, v90
	s_nop 1
	v_addc_co_u32_e32 v83, vcc, 0, v91, vcc
	s_andn2_b64 vcc, exec, s[66:67]
	s_waitcnt lgkmcnt(0)
	global_store_dwordx4 v[82:83], v[86:89], off offset:2048
	s_barrier
	ds_write_b128 v180, v[226:229]
	ds_write_b128 v180, v[230:233] offset:1024
	s_cbranch_vccnz .LBB0_1336
	v_lshlrev_b32_e32 v82, 16, v38
	v_and_b32_e32 v83, 0xffff0000, v38
	v_lshlrev_b32_e32 v84, 16, v39
	v_and_b32_e32 v85, 0xffff0000, v39
	v_pk_mul_f32 v[82:83], v[122:123], v[82:83] op_sel_hi:[0,1]
	v_pk_mul_f32 v[84:85], v[122:123], v[84:85] op_sel_hi:[0,1]
	v_cvt_pk_bf16_f32 v82, v82, v83
	v_cvt_pk_bf16_f32 v83, v84, v85
	v_lshlrev_b32_e32 v84, 16, v40
	v_and_b32_e32 v85, 0xffff0000, v40
	v_lshlrev_b32_e32 v86, 16, v41
	v_and_b32_e32 v87, 0xffff0000, v41
	v_pk_mul_f32 v[84:85], v[122:123], v[84:85] op_sel_hi:[0,1]
	v_pk_mul_f32 v[86:87], v[122:123], v[86:87] op_sel_hi:[0,1]
	v_cvt_pk_bf16_f32 v84, v84, v85
	v_cvt_pk_bf16_f32 v85, v86, v87
	ds_write_b128 v127, v[82:85] offset:17408
	ds_write_b128 v127, v[42:45] offset:52224
	s_and_saveexec_b64 s[66:67], s[10:11]
	s_cbranch_execz .LBB0_1364
	v_lshlrev_b32_e32 v82, 16, v34
	v_and_b32_e32 v83, 0xffff0000, v34
	v_lshlrev_b32_e32 v84, 16, v35
	v_and_b32_e32 v85, 0xffff0000, v35
	v_pk_mul_f32 v[82:83], v[124:125], v[82:83] op_sel_hi:[0,1]
	v_pk_mul_f32 v[84:85], v[124:125], v[84:85] op_sel_hi:[0,1]
	v_cvt_pk_bf16_f32 v82, v82, v83
	v_cvt_pk_bf16_f32 v83, v84, v85
	v_lshlrev_b32_e32 v84, 16, v36
	v_and_b32_e32 v85, 0xffff0000, v36
	v_lshlrev_b32_e32 v86, 16, v37
	v_and_b32_e32 v87, 0xffff0000, v37
	v_pk_mul_f32 v[84:85], v[124:125], v[84:85] op_sel_hi:[0,1]
	v_pk_mul_f32 v[86:87], v[124:125], v[86:87] op_sel_hi:[0,1]
	v_cvt_pk_bf16_f32 v84, v84, v85
	v_cvt_pk_bf16_f32 v85, v86, v87
	ds_write_b128 v127, v[82:85] offset:26112
	s_or_b64 exec, exec, s[66:67]
	ds_write_b128 v127, v[54:57] offset:60928
	s_and_saveexec_b64 s[66:67], s[12:13]
	s_cbranch_execnz .LBB0_1365
